# final RMSNorm row loop: both halves' loads issued together (one memory round trip per row instead of two), rsqrt via v_sqrt+v_rcp
# speedup vs baseline: 1.0055x; 1.0055x over previous
; DI float bf_lo(unsigned w) { return __uint_as_float(w << 16); }
; DI float bf_hi(unsigned w) { return __uint_as_float(w & 0xffff0000u); }
; DI void final_row(const bf16_t* hrow, const float* prow, const float* g, float* orow, int lane) {
;     const float pv = (lane < 16) ? prow[lane] : 0.f;
;     const float r = 1.0f / sqrtf(wave_sum(pv) * (1.f / DM) + NORM_EPS);
; #pragma unroll
;     for (int j = 0; j < 2; ++j) {
;         const int c0 = j * 512 + lane * 8;
;         const u32x4 w = *(const u32x4*)(hrow + c0);
;         const f32x4 g0 = *(const f32x4*)(g + c0), g1 = *(const f32x4*)(g + c0 + 4);
;         *(f32x4*)(orow + c0) = (f32x4){bf_lo(w.x) * r * g0.x, bf_hi(w.x) * r * g0.y, bf_lo(w.y) * r * g0.z, bf_hi(w.y) * r * g0.w};
;         *(f32x4*)(orow + c0 + 4) = (f32x4){bf_lo(w.z) * r * g1.x, bf_hi(w.z) * r * g1.y, bf_lo(w.w) * r * g1.z, bf_hi(w.w) * r * g1.w};
;     }
; }
; template <int l> DI void layer_phases(unsigned char* lds, unsigned* xb_st, const int lo, const int hi_ph) {
;     ...
;             if (IN(ph)) { CTX for (int m = gw; m < NT; m += ngw) final_row(pATT + (size_t)m * DM, pPB + (size_t)m * 16, A.in[19], out + (size_t)m * DM, lane); }
.LBB0_1824:
	s_or_b64 exec, exec, s[2:3]
	global_load_dwordx4 v[18:21], v[4:5], off offset:-1024
	global_load_dwordx4 v[22:25], v[0:1], off
	global_load_dwordx4 v[26:29], v[0:1], off offset:16
	global_load_dwordx4 v[36:39], v[4:5], off
	global_load_dwordx4 v[40:43], v[0:1], off offset:2048
	global_load_dwordx4 v[44:47], v[0:1], off offset:2064
	s_waitcnt vmcnt(6)
	ds_bpermute_b32 v17, v8, v16
	s_add_i32 s8, s8, s10
	v_lshl_add_u64 v[2:3], v[2:3], 0, s[4:5]
	s_cmp_lt_i32 s8, 0x8000
	s_waitcnt lgkmcnt(0)
	v_add_f32_e32 v16, v16, v17
	ds_bpermute_b32 v17, v9, v16
	s_waitcnt lgkmcnt(0)
	v_add_f32_e32 v16, v16, v17
	ds_bpermute_b32 v17, v10, v16
	s_waitcnt lgkmcnt(0)
	v_add_f32_e32 v16, v16, v17
	ds_bpermute_b32 v17, v11, v16
	s_waitcnt lgkmcnt(0)
	v_add_f32_e32 v16, v16, v17
	ds_bpermute_b32 v17, v12, v16
	s_waitcnt lgkmcnt(0)
	v_add_f32_e32 v16, v16, v17
	ds_bpermute_b32 v17, v13, v16
	s_waitcnt lgkmcnt(0)
	v_add_f32_e32 v16, v16, v17
	v_fmamk_f32 v16, v16, 0x3a800000, v14
	v_mul_f32_e32 v17, 0x4f800000, v16
	v_cmp_gt_f32_e32 vcc, s9, v16
	s_nop 1
	v_cndmask_b32_e32 v16, v16, v17, vcc
	v_sqrt_f32_e32 v17, v16
	s_nop 0
	s_nop 1
	v_mul_f32_e32 v30, 0x37800000, v17
	v_cndmask_b32_e32 v17, v17, v30, vcc
	v_cmp_class_f32_e32 vcc, v16, v15
	s_nop 1
	v_cndmask_b32_e32 v16, v17, v16, vcc
	v_div_scale_f32 v17, s[2:3], v16, v16, 1.0
	v_div_scale_f32 v31, vcc, 1.0, v16, 1.0
	v_rcp_f32_e32 v17, v16
	s_nop 0
	v_mul_f32_e32 v30, 1.0, v17
	s_waitcnt vmcnt(5)
	v_lshlrev_b32_e32 v16, 16, v18
	v_and_b32_e32 v17, 0xffff0000, v18
	v_lshlrev_b32_e32 v18, 16, v19
	v_and_b32_e32 v19, 0xffff0000, v19
	v_lshlrev_b32_e32 v32, 16, v20
	v_and_b32_e32 v33, 0xffff0000, v20
	v_lshlrev_b32_e32 v20, 16, v21
	v_and_b32_e32 v21, 0xffff0000, v21
	v_pk_mul_f32 v[16:17], v[30:31], v[16:17] op_sel_hi:[0,1]
	v_pk_mul_f32 v[18:19], v[30:31], v[18:19] op_sel_hi:[0,1]
	v_pk_mul_f32 v[32:33], v[30:31], v[32:33] op_sel_hi:[0,1]
	v_pk_mul_f32 v[34:35], v[30:31], v[20:21] op_sel_hi:[0,1]
	s_waitcnt vmcnt(4)
	v_pk_mul_f32 v[16:17], v[22:23], v[16:17]
	v_pk_mul_f32 v[18:19], v[24:25], v[18:19]
	s_waitcnt vmcnt(3)
	v_pk_mul_f32 v[20:21], v[26:27], v[32:33]
	v_pk_mul_f32 v[22:23], v[28:29], v[34:35]
	global_store_dwordx4 v[6:7], v[16:19], off
	global_store_dwordx4 v[6:7], v[20:23], off offset:16
	v_lshl_add_u64 v[4:5], v[4:5], 0, s[12:13]
	s_waitcnt vmcnt(4)
	v_lshlrev_b32_e32 v28, 16, v36
	v_and_b32_e32 v29, 0xffff0000, v36
	v_lshlrev_b32_e32 v16, 16, v37
	v_and_b32_e32 v17, 0xffff0000, v37
	v_lshlrev_b32_e32 v32, 16, v38
	v_and_b32_e32 v33, 0xffff0000, v38
	v_lshlrev_b32_e32 v18, 16, v39
	v_and_b32_e32 v19, 0xffff0000, v39
	v_pk_mul_f32 v[28:29], v[30:31], v[28:29] op_sel_hi:[0,1]
	v_pk_mul_f32 v[34:35], v[30:31], v[16:17] op_sel_hi:[0,1]
	v_pk_mul_f32 v[32:33], v[30:31], v[32:33] op_sel_hi:[0,1]
	v_pk_mul_f32 v[30:31], v[30:31], v[18:19] op_sel_hi:[0,1]
	s_waitcnt vmcnt(3)
	v_pk_mul_f32 v[16:17], v[40:41], v[28:29]
	v_pk_mul_f32 v[18:19], v[42:43], v[34:35]
	s_waitcnt vmcnt(2)
	v_pk_mul_f32 v[20:21], v[44:45], v[32:33]
	v_pk_mul_f32 v[22:23], v[46:47], v[30:31]
	global_store_dwordx4 v[6:7], v[16:19], off offset:2048
	global_store_dwordx4 v[6:7], v[20:23], off offset:2064
	v_lshl_add_u64 v[6:7], v[6:7], 0, s[6:7]
	s_cbranch_scc0 .LBB0_1827
